# hgrn_rec loop tail: counted waits no longer cover the output-store acks; prep2 gain-vector loads issued ahead of each pass
# speedup vs baseline: 1.0063x; 1.0010x over previous
; __device__ __forceinline__ float bflo(unsigned w) { return __uint_as_float(w << 16); }
; __device__ __forceinline__ float bfhi(unsigned w) { return __uint_as_float(w & 0xffff0000u); }
; __device__ __forceinline__ void norm64_inplace(bf16* p, const float* gain, float mult) {
;     u32x4 w[8]; float ss = 0.f;
; #pragma unroll
;     for (int k = 0; k < 8; ++k) { w[k] = ((const u32x4*)p)[k];
;         const float a0 = bflo(w[k].x), a1 = bfhi(w[k].x), a2 = bflo(w[k].y), a3 = bfhi(w[k].y), a4 = bflo(w[k].z), a5 = bfhi(w[k].z), a6 = bflo(w[k].w), a7 = bfhi(w[k].w);
;         ss += (a0 * a0 + a1 * a1) + (a2 * a2 + a3 * a3) + (a4 * a4 + a5 * a5) + (a6 * a6 + a7 * a7); }
;     const float r = rsqrtf(ss * (1.0f / 64.0f) + EPS) * mult;
; __device__ __forceinline__ void nsa_prep2_phase(bf16* z, const float* qg, const float* kg, bf16* vst, bf16* vwt, LAS unsigned char* lds, int tid, int u0, int ustride) {
;     ...
;         { const int tok = tid >> 3, wh = (tid >> 2) & 1, g = tid & 3; norm64_inplace(z + (row0 + tok) * ZP + (wh ? C_KW : C_KS) + g * 64, kg, 1.0f); }
.LBB0_687:
	s_or_b64 exec, exec, s[20:21]
	v_mad_u64_u32 v[4:5], s[4:5], v30, s88, 0
	v_mad_i32_i24 v5, v31, s88, v5
	v_lshl_add_u64 v[44:45], v[34:35], 0, v[4:5]
	global_load_dwordx4 v[130:133], v3, s[10:11]
	global_load_dwordx4 v[134:137], v3, s[10:11] offset:16
	global_load_dwordx4 v[138:141], v3, s[10:11] offset:32
	global_load_dwordx4 v[142:145], v3, s[10:11] offset:48
	global_load_dwordx4 v[146:149], v3, s[10:11] offset:64
	global_load_dwordx4 v[150:153], v3, s[10:11] offset:80
	global_load_dwordx4 v[154:157], v3, s[10:11] offset:96
	global_load_dwordx4 v[158:161], v3, s[10:11] offset:112
	global_load_dwordx4 v[162:165], v3, s[10:11] offset:128
	global_load_dwordx4 v[166:169], v3, s[10:11] offset:144
	global_load_dwordx4 v[170:173], v3, s[10:11] offset:160
	global_load_dwordx4 v[186:189], v3, s[10:11] offset:176
	global_load_dwordx4 v[190:193], v3, s[10:11] offset:192
	global_load_dwordx4 v[194:197], v3, s[10:11] offset:208
	global_load_dwordx4 v[198:201], v3, s[10:11] offset:224
	global_load_dwordx4 v[202:205], v3, s[10:11] offset:240
	global_load_dwordx4 v[8:11], v[44:45], off offset:48
	global_load_dwordx4 v[12:15], v[44:45], off offset:32
	global_load_dwordx4 v[28:31], v[44:45], off
	global_load_dwordx4 v[4:7], v[44:45], off offset:16
	s_lshl_b32 s4, s16, 2
	s_ashr_i32 s5, s4, 31
	s_lshl_b64 s[6:7], s[4:5], 18
	s_lshl_b32 s68, s1, 1
	v_mov_b32_e32 v43, v3
	s_or_b32 s16, s4, 1
	s_ashr_i32 s17, s16, 31
	s_lshl_b64 s[16:17], s[16:17], 18
	s_or_b32 s18, s4, 2
	s_ashr_i32 s19, s18, 31
	s_lshl_b64 s[18:19], s[18:19], 18
	s_or_b32 s4, s4, 3
	s_ashr_i32 s5, s4, 31
	s_lshl_b64 s[4:5], s[4:5], 18
	s_add_i32 s1, s0, 0x80
	s_cmpk_gt_i32 s0, 0x7f
	s_waitcnt vmcnt(3)
	v_lshlrev_b32_e32 v113, 16, v8
	s_waitcnt vmcnt(2)
	v_lshlrev_b32_e32 v58, 16, v12
	v_and_b32_e32 v59, 0xffff0000, v12
	s_waitcnt vmcnt(0)
	v_and_b32_e32 v63, 0xffff0000, v5
	v_and_b32_e32 v62, 0xffff0000, v4
	v_lshlrev_b32_e32 v79, 16, v5
	v_lshlrev_b32_e32 v78, 16, v4
	v_pk_mul_f32 v[4:5], v[62:63], v[62:63]
	v_and_b32_e32 v61, 0xffff0000, v7
	v_and_b32_e32 v60, 0xffff0000, v6
	v_pk_fma_f32 v[4:5], v[78:79], v[78:79], v[4:5]
	v_lshlrev_b32_e32 v81, 16, v7
	v_lshlrev_b32_e32 v80, 16, v6
	v_pk_mul_f32 v[6:7], v[60:61], v[60:61]
	v_pk_add_f32 v[4:5], v[4:5], v[4:5] op_sel:[0,1] op_sel_hi:[1,0]
	v_pk_fma_f32 v[6:7], v[80:81], v[80:81], v[6:7]
	v_lshlrev_b32_e32 v56, 16, v13
	v_pk_add_f32 v[4:5], v[6:7], v[4:5]
	v_and_b32_e32 v57, 0xffff0000, v13
	v_pk_add_f32 v[68:69], v[6:7], v[4:5] op_sel:[1,0] op_sel_hi:[0,1]
	global_load_dwordx4 v[4:7], v[44:45], off offset:112
	global_load_dwordx4 v[16:19], v[44:45], off offset:96
	global_load_dwordx4 v[20:23], v[44:45], off offset:80
	global_load_dwordx4 v[24:27], v[44:45], off offset:64
	v_mul_f32_e32 v2, v59, v59
	v_pk_fma_f32 v[64:65], v[58:59], v[58:59], v[2:3] op_sel_hi:[1,1,0]
	v_mul_f32_e32 v2, v57, v57
	v_pk_fma_f32 v[66:67], v[56:57], v[56:57], v[2:3] op_sel_hi:[1,1,0]
	v_and_b32_e32 v95, 0xffff0000, v31
	v_and_b32_e32 v97, 0xffff0000, v30
	v_and_b32_e32 v101, 0xffff0000, v28
	v_lshlrev_b32_e32 v94, 16, v31
	v_lshlrev_b32_e32 v96, 16, v30
	v_and_b32_e32 v99, 0xffff0000, v29
	v_lshlrev_b32_e32 v100, 16, v28
	v_mov_b32_e32 v30, v97
	v_mov_b32_e32 v31, v101
	v_lshlrev_b32_e32 v98, 16, v29
	v_mov_b32_e32 v28, v96
	v_mov_b32_e32 v29, v100
	v_pk_mul_f32 v[30:31], v[30:31], v[30:31]
	v_mov_b32_e32 v106, v80
	v_pk_fma_f32 v[28:29], v[28:29], v[28:29], v[30:31]
	v_mov_b32_e32 v107, v60
	v_mov_b32_e32 v60, v81
	v_lshlrev_b32_e32 v80, 16, v9
	v_and_b32_e32 v81, 0xffff0000, v9
	v_and_b32_e32 v93, 0xffff0000, v8
	v_and_b32_e32 v92, 0xffff0000, v14
	v_pk_mul_f32 v[8:9], v[80:81], v[80:81]
	v_lshlrev_b32_e32 v112, 16, v14
	v_lshlrev_b32_e32 v115, 16, v10
	v_lshlrev_b32_e32 v114, 16, v15
	v_mov_b32_e32 v110, v78
	v_lshlrev_b32_e32 v78, 16, v11
	v_mov_b32_e32 v65, v8
	v_mov_b32_e32 v67, v9
	v_mov_b32_e32 v111, v62
	v_mov_b32_e32 v62, v79
	v_pk_add_f32 v[8:9], v[64:65], v[66:67]
	v_mov_b32_e32 v104, v112
	v_mov_b32_e32 v105, v92
	s_waitcnt vmcnt(2)
	v_and_b32_e32 v47, 0xffff0000, v16
	s_waitcnt vmcnt(1)
	v_and_b32_e32 v51, 0xffff0000, v21
	s_waitcnt vmcnt(0)
	v_and_b32_e32 v55, 0xffff0000, v25
	v_and_b32_e32 v54, 0xffff0000, v24
	v_lshlrev_b32_e32 v83, 16, v25
	v_lshlrev_b32_e32 v82, 16, v24
	v_pk_mul_f32 v[12:13], v[54:55], v[54:55]
	v_and_b32_e32 v53, 0xffff0000, v27
	v_and_b32_e32 v52, 0xffff0000, v26
	v_pk_fma_f32 v[12:13], v[82:83], v[82:83], v[12:13]
	v_lshlrev_b32_e32 v85, 16, v27
	v_lshlrev_b32_e32 v84, 16, v26
	v_pk_mul_f32 v[24:25], v[52:53], v[52:53]
	v_pk_add_f32 v[12:13], v[12:13], v[12:13] op_sel:[0,1] op_sel_hi:[1,0]
	v_pk_fma_f32 v[24:25], v[84:85], v[84:85], v[24:25]
	v_and_b32_e32 v50, 0xffff0000, v20
	v_pk_add_f32 v[12:13], v[24:25], v[12:13]
	v_lshlrev_b32_e32 v87, 16, v21
	v_pk_add_f32 v[70:71], v[24:25], v[12:13] op_sel:[1,0] op_sel_hi:[0,1]
	v_lshlrev_b32_e32 v86, 16, v20
	v_pk_mul_f32 v[12:13], v[50:51], v[50:51]
	v_and_b32_e32 v49, 0xffff0000, v23
	v_and_b32_e32 v48, 0xffff0000, v22
	v_pk_fma_f32 v[12:13], v[86:87], v[86:87], v[12:13]
	v_lshlrev_b32_e32 v89, 16, v23
	v_lshlrev_b32_e32 v88, 16, v22
	v_pk_mul_f32 v[20:21], v[48:49], v[48:49]
	v_pk_add_f32 v[12:13], v[12:13], v[12:13] op_sel:[0,1] op_sel_hi:[1,0]
	v_pk_fma_f32 v[20:21], v[88:89], v[88:89], v[20:21]
	v_lshlrev_b32_e32 v46, 16, v16
	v_pk_add_f32 v[12:13], v[20:21], v[12:13]
	v_mul_f32_e32 v2, v47, v47
	v_pk_add_f32 v[76:77], v[20:21], v[12:13] op_sel:[1,0] op_sel_hi:[0,1]
	s_waitcnt vmcnt(0)
; __device__ __forceinline__ float bflo(unsigned w) { return __uint_as_float(w << 16); }
; __device__ __forceinline__ float bfhi(unsigned w) { return __uint_as_float(w & 0xffff0000u); }
; __device__ __forceinline__ unsigned pk2(float lo, float hi) { return pg8::cvt_pk_bf16(lo, hi); }
; __device__ __forceinline__ void norm64_inplace(bf16* p, const float* gain, float mult) {
;     ...
;     const float r = rsqrtf(ss * (1.0f / 64.0f) + EPS) * mult;
; #pragma unroll
;     for (int k = 0; k < 8; ++k) { const f32x4 g0 = *(const f32x4*)(gain + 8 * k), g1 = *(const f32x4*)(gain + 8 * k + 4);
;         u32x4 o; o.x = pk2(bflo(w[k].x) * r * g0[0], bfhi(w[k].x) * r * g0[1]); o.y = pk2(bflo(w[k].y) * r * g0[2], bfhi(w[k].y) * r * g0[3]);
;         o.z = pk2(bflo(w[k].z) * r * g1[0], bfhi(w[k].z) * r * g1[1]); o.w = pk2(bflo(w[k].w) * r * g1[2], bfhi(w[k].w) * r * g1[3]);
;         ((u32x4*)p)[k] = o; }
	v_mov_b64_e32 v[20:21], v[134:135]
	v_mov_b64_e32 v[22:23], v[136:137]
	v_mov_b64_e32 v[24:25], v[130:131]
	v_mov_b64_e32 v[26:27], v[132:133]
	v_and_b32_e32 v13, 0xffff0000, v17
	v_pk_fma_f32 v[72:73], v[46:47], v[46:47], v[2:3] op_sel_hi:[1,1,0]
	v_lshlrev_b32_e32 v12, 16, v17
	v_mul_f32_e32 v2, v13, v13
	v_pk_fma_f32 v[74:75], v[12:13], v[12:13], v[2:3] op_sel_hi:[1,1,0]
	v_mul_f32_e32 v2, v95, v95
	v_pk_fma_f32 v[108:109], v[94:95], v[94:95], v[2:3] op_sel_hi:[1,1,0]
	v_mul_f32_e32 v2, v99, v99
	v_pk_fma_f32 v[16:17], v[98:99], v[98:99], v[2:3] op_sel_hi:[1,1,0]
	v_pk_mov_b32 v[102:103], v[18:19], v[6:7] op_sel:[1,0]
	v_pk_add_f32 v[16:17], v[28:29], v[16:17] op_sel:[1,0] op_sel_hi:[0,1]
	v_pk_add_f32 v[30:31], v[28:29], v[16:17]
	v_pk_mov_b32 v[16:17], v[14:15], v[10:11] op_sel:[1,0]
	v_pk_mul_f32 v[14:15], v[92:93], v[92:93]
	v_and_b32_e32 v91, 0xffff0000, v17
	v_and_b32_e32 v90, 0xffff0000, v16
	v_and_b32_e32 v11, 0xffff0000, v11
	v_and_b32_e32 v10, s0, v10
	v_pk_fma_f32 v[116:117], v[112:113], v[112:113], v[14:15]
	v_pk_mul_f32 v[14:15], v[90:91], v[90:91]
	v_mov_b32_e32 v79, v11
	v_pk_mul_f32 v[10:11], v[10:11], v[10:11]
	v_pk_add_f32 v[30:31], v[108:109], v[30:31]
	v_pk_fma_f32 v[122:123], v[114:115], v[114:115], v[14:15]
	v_mul_f32_e32 v31, v78, v78
	v_mov_b32_e32 v69, v11
	v_pk_add_f32 v[8:9], v[116:117], v[8:9]
	v_pk_add_f32 v[10:11], v[30:31], v[68:69]
	v_pk_add_f32 v[8:9], v[122:123], v[8:9]
	v_lshlrev_b32_e32 v29, 16, v6
	v_pk_add_f32 v[8:9], v[10:11], v[8:9]
	v_lshlrev_b32_e32 v6, 16, v7
	v_pk_add_f32 v[108:109], v[8:9], v[8:9] op_sel:[0,1] op_sel_hi:[1,0]
	v_and_b32_e32 v7, 0xffff0000, v7
	v_pk_add_f32 v[70:71], v[108:109], v[70:71]
	v_lshlrev_b32_e32 v15, 16, v4
	v_and_b32_e32 v17, 0xffff0000, v4
	v_mul_f32_e32 v77, v7, v7
	v_mul_f32_e32 v71, v6, v6
	v_lshlrev_b32_e32 v4, 16, v5
	v_and_b32_e32 v5, 0xffff0000, v5
	v_and_b32_e32 v16, 0xffff0000, v18
	v_pk_add_f32 v[70:71], v[70:71], v[76:77]
	v_pk_mul_f32 v[76:77], v[4:5], v[4:5]
	v_lshlrev_b32_e32 v14, 16, v18
	v_lshlrev_b32_e32 v28, 16, v19
	v_and_b32_e32 v19, 0xffff0000, v103
	v_and_b32_e32 v18, 0xffff0000, v102
	v_pk_mul_f32 v[102:103], v[16:17], v[16:17]
	v_mov_b32_e32 v73, v76
	v_mov_b32_e32 v75, v77
	v_pk_fma_f32 v[124:125], v[14:15], v[14:15], v[102:103]
	v_pk_mul_f32 v[102:103], v[18:19], v[18:19]
	v_pk_add_f32 v[72:73], v[72:73], v[74:75]
	v_pk_fma_f32 v[126:127], v[28:29], v[28:29], v[102:103]
	v_pk_add_f32 v[72:73], v[124:125], v[72:73]
	v_mov_b32_e32 v10, v14
	v_pk_add_f32 v[72:73], v[126:127], v[72:73]
	v_mov_b32_e32 v102, v114
	v_pk_add_f32 v[70:71], v[70:71], v[72:73]
	v_mov_b32_e32 v103, v90
	v_add_f32_e32 v2, v70, v71
	v_fmamk_f32 v2, v2, 0x3c800000, v213
	v_cmp_gt_f32_e32 vcc, s83, v2
	v_mul_f32_e32 v14, 0x4b800000, v2
	v_mov_b32_e32 v92, v113
	v_cndmask_b32_e32 v2, v2, v14, vcc
	v_rsq_f32_e32 v2, v2
	v_mov_b32_e32 v90, v115
	v_mov_b32_e32 v68, v82
	v_mov_b32_e32 v69, v54
	v_mul_f32_e32 v14, 0x45800000, v2
	v_cndmask_b32_e32 v2, v2, v14, vcc
	v_pk_mul_f32 v[70:71], v[2:3], v[100:101] op_sel_hi:[0,1]
	v_pk_mul_f32 v[62:63], v[2:3], v[62:63] op_sel_hi:[0,1]
	v_pk_mul_f32 v[58:59], v[2:3], v[58:59] op_sel_hi:[0,1]
	v_pk_mul_f32 v[56:57], v[2:3], v[56:57] op_sel_hi:[0,1]
	v_mov_b32_e32 v54, v83
	v_pk_mul_f32 v[54:55], v[2:3], v[54:55] op_sel_hi:[0,1]
	v_pk_mul_f32 v[24:25], v[24:25], v[70:71]
	v_pk_mul_f32 v[70:71], v[2:3], v[98:99] op_sel_hi:[0,1]
	v_pk_mul_f32 v[26:27], v[26:27], v[70:71]
	v_cvt_pk_bf16_f32 v24, v24, v25
	v_cvt_pk_bf16_f32 v25, v26, v27
	v_pk_mul_f32 v[26:27], v[2:3], v[96:97] op_sel_hi:[0,1]
	v_pk_mul_f32 v[20:21], v[20:21], v[26:27]
	v_pk_mul_f32 v[70:71], v[2:3], v[110:111] op_sel_hi:[0,1]
	v_cvt_pk_bf16_f32 v26, v20, v21
	v_pk_mul_f32 v[20:21], v[2:3], v[94:95] op_sel_hi:[0,1]
	v_pk_mul_f32 v[20:21], v[22:23], v[20:21]
	v_mov_b32_e32 v66, v84
	v_cvt_pk_bf16_f32 v27, v20, v21
	global_store_dwordx4 v[44:45], v[24:27], off
	v_mov_b64_e32 v[20:21], v[142:143]
	v_mov_b64_e32 v[22:23], v[144:145]
	s_nop 0
	v_mov_b64_e32 v[24:25], v[138:139]
	v_mov_b64_e32 v[26:27], v[140:141]
	v_mov_b32_e32 v67, v52
	v_mov_b32_e32 v52, v85
	v_mov_b32_e32 v64, v86
	v_mov_b32_e32 v65, v50
	v_mov_b32_e32 v50, v87
	v_pk_mul_f32 v[50:51], v[2:3], v[50:51] op_sel_hi:[0,1]
	v_mov_b32_e32 v30, v88
	v_mov_b32_e32 v31, v48
	v_mov_b32_e32 v48, v89
	v_mov_b32_e32 v11, v16
	v_mov_b32_e32 v8, v28
	v_mov_b32_e32 v9, v18
	v_pk_mul_f32 v[12:13], v[2:3], v[12:13] op_sel_hi:[0,1]
	v_pk_mul_f32 v[10:11], v[2:3], v[10:11] op_sel_hi:[0,1]
	v_pk_mul_f32 v[8:9], v[2:3], v[8:9] op_sel_hi:[0,1]
	v_mov_b32_e32 v16, v15
	v_pk_mul_f32 v[4:5], v[2:3], v[4:5] op_sel_hi:[0,1]
	v_mov_b32_e32 v18, v29
	s_mov_b32 s0, s1
	v_pk_mul_f32 v[24:25], v[24:25], v[70:71]
	v_pk_mul_f32 v[26:27], v[26:27], v[62:63]
	v_cvt_pk_bf16_f32 v24, v24, v25
	v_cvt_pk_bf16_f32 v25, v26, v27
	v_pk_mul_f32 v[26:27], v[2:3], v[106:107] op_sel_hi:[0,1]
	v_pk_mul_f32 v[20:21], v[20:21], v[26:27]
	s_nop 0
	v_cvt_pk_bf16_f32 v26, v20, v21
	v_pk_mul_f32 v[20:21], v[2:3], v[60:61] op_sel_hi:[0,1]
	v_pk_mul_f32 v[20:21], v[22:23], v[20:21]
	s_nop 0
	v_cvt_pk_bf16_f32 v27, v20, v21
	global_store_dwordx4 v[44:45], v[24:27], off offset:16
	v_mov_b64_e32 v[20:21], v[150:151]
	v_mov_b64_e32 v[22:23], v[152:153]
	s_nop 0
	v_mov_b64_e32 v[24:25], v[146:147]
	v_mov_b64_e32 v[26:27], v[148:149]
	v_pk_mul_f32 v[24:25], v[24:25], v[58:59]
	v_pk_mul_f32 v[26:27], v[26:27], v[56:57]
	v_cvt_pk_bf16_f32 v24, v24, v25
	v_cvt_pk_bf16_f32 v25, v26, v27
	v_pk_mul_f32 v[26:27], v[2:3], v[104:105] op_sel_hi:[0,1]
	v_pk_mul_f32 v[20:21], v[20:21], v[26:27]
; #define LAS __attribute__((address_space(3)))
; __device__ __forceinline__ float bflo(unsigned w) { return __uint_as_float(w << 16); }
; __device__ __forceinline__ float bfhi(unsigned w) { return __uint_as_float(w & 0xffff0000u); }
; __device__ __forceinline__ unsigned pk2(float lo, float hi) { return pg8::cvt_pk_bf16(lo, hi); }
; __device__ __forceinline__ void norm64_inplace(bf16* p, const float* gain, float mult) {
;     ...
;     for (int k = 0; k < 8; ++k) { const f32x4 g0 = *(const f32x4*)(gain + 8 * k), g1 = *(const f32x4*)(gain + 8 * k + 4);
;         u32x4 o; o.x = pk2(bflo(w[k].x) * r * g0[0], bfhi(w[k].x) * r * g0[1]); o.y = pk2(bflo(w[k].y) * r * g0[2], bfhi(w[k].y) * r * g0[3]);
;         o.z = pk2(bflo(w[k].z) * r * g1[0], bfhi(w[k].z) * r * g1[1]); o.w = pk2(bflo(w[k].w) * r * g1[2], bfhi(w[k].w) * r * g1[3]);
;         ((u32x4*)p)[k] = o; }
; __device__ __forceinline__ void nsa_prep2_phase(bf16* z, const float* qg, const float* kg, bf16* vst, bf16* vwt, LAS unsigned char* lds, int tid, int u0, int ustride) {
;     ...
;         { const int d = tid >> 3, ch = tid & 7;
; #pragma unroll
;           for (int ti = 0; ti < 8; ++ti) { const int g = ti & 3; bf16* dst = (ti >> 2) ? vwt : vst;
;               const u32x4 w = *(const LAS u32x4*)(lds + ti * TILEB + d * TPITCH + ch * 16);
;               *(u32x4*)(dst + ((size_t)(b * 4 + g) * 64 + d) * SEQ + tb * 64 + ch * 8) = w; } }
;         __syncthreads();
	v_pk_mul_f32 v[56:57], v[2:3], v[92:93] op_sel_hi:[0,1]
	v_cvt_pk_bf16_f32 v26, v20, v21
	v_pk_mul_f32 v[20:21], v[2:3], v[102:103] op_sel_hi:[0,1]
	v_pk_mul_f32 v[20:21], v[22:23], v[20:21]
	s_nop 0
	v_cvt_pk_bf16_f32 v27, v20, v21
	global_store_dwordx4 v[44:45], v[24:27], off offset:32
	v_mov_b64_e32 v[20:21], v[158:159]
	v_mov_b64_e32 v[22:23], v[160:161]
	s_nop 0
	v_mov_b64_e32 v[24:25], v[154:155]
	v_mov_b64_e32 v[26:27], v[156:157]
	v_pk_mul_f32 v[24:25], v[24:25], v[56:57]
	v_pk_mul_f32 v[56:57], v[2:3], v[80:81] op_sel_hi:[0,1]
	v_pk_mul_f32 v[26:27], v[26:27], v[56:57]
	v_cvt_pk_bf16_f32 v24, v24, v25
	v_cvt_pk_bf16_f32 v25, v26, v27
	v_pk_mul_f32 v[26:27], v[2:3], v[90:91] op_sel_hi:[0,1]
	v_pk_mul_f32 v[20:21], v[20:21], v[26:27]
	v_pk_mul_f32 v[56:57], v[2:3], v[68:69] op_sel_hi:[0,1]
	v_cvt_pk_bf16_f32 v26, v20, v21
	v_pk_mul_f32 v[20:21], v[2:3], v[78:79] op_sel_hi:[0,1]
	v_pk_mul_f32 v[20:21], v[22:23], v[20:21]
	s_nop 0
	v_cvt_pk_bf16_f32 v27, v20, v21
	global_store_dwordx4 v[44:45], v[24:27], off offset:48
	v_mov_b64_e32 v[20:21], v[166:167]
	v_mov_b64_e32 v[22:23], v[168:169]
	s_nop 0
	v_mov_b64_e32 v[24:25], v[162:163]
	v_mov_b64_e32 v[26:27], v[164:165]
	v_pk_mul_f32 v[24:25], v[24:25], v[56:57]
	v_pk_mul_f32 v[26:27], v[26:27], v[54:55]
	v_cvt_pk_bf16_f32 v24, v24, v25
	v_cvt_pk_bf16_f32 v25, v26, v27
	v_pk_mul_f32 v[26:27], v[2:3], v[66:67] op_sel_hi:[0,1]
	v_pk_mul_f32 v[20:21], v[20:21], v[26:27]
	s_nop 0
	v_cvt_pk_bf16_f32 v26, v20, v21
	v_pk_mul_f32 v[20:21], v[2:3], v[52:53] op_sel_hi:[0,1]
	v_pk_mul_f32 v[20:21], v[22:23], v[20:21]
	v_pk_mul_f32 v[52:53], v[2:3], v[64:65] op_sel_hi:[0,1]
	v_cvt_pk_bf16_f32 v27, v20, v21
	global_store_dwordx4 v[44:45], v[24:27], off offset:64
	v_mov_b64_e32 v[20:21], v[186:187]
	v_mov_b64_e32 v[22:23], v[188:189]
	s_nop 0
	v_mov_b64_e32 v[24:25], v[170:171]
	v_mov_b64_e32 v[26:27], v[172:173]
	v_pk_mul_f32 v[24:25], v[52:53], v[24:25]
	v_pk_mul_f32 v[26:27], v[50:51], v[26:27]
	v_cvt_pk_bf16_f32 v24, v24, v25
	v_cvt_pk_bf16_f32 v25, v26, v27
	v_pk_mul_f32 v[26:27], v[2:3], v[30:31] op_sel_hi:[0,1]
	v_pk_mul_f32 v[20:21], v[26:27], v[20:21]
	v_pk_mul_f32 v[30:31], v[2:3], v[46:47] op_sel_hi:[0,1]
	v_cvt_pk_bf16_f32 v26, v20, v21
	v_pk_mul_f32 v[20:21], v[2:3], v[48:49] op_sel_hi:[0,1]
	v_pk_mul_f32 v[20:21], v[20:21], v[22:23]
	s_nop 0
	v_cvt_pk_bf16_f32 v27, v20, v21
	global_store_dwordx4 v[44:45], v[24:27], off offset:80
	v_mov_b64_e32 v[20:21], v[194:195]
	v_mov_b64_e32 v[22:23], v[196:197]
	s_nop 0
	v_mov_b64_e32 v[24:25], v[190:191]
	v_mov_b64_e32 v[26:27], v[192:193]
	v_pk_mul_f32 v[10:11], v[10:11], v[20:21]
	v_pk_mul_f32 v[24:25], v[30:31], v[24:25]
	v_pk_mul_f32 v[12:13], v[12:13], v[26:27]
	v_pk_mul_f32 v[8:9], v[8:9], v[22:23]
	v_cvt_pk_bf16_f32 v24, v24, v25
	v_cvt_pk_bf16_f32 v25, v12, v13
	v_cvt_pk_bf16_f32 v26, v10, v11
	v_cvt_pk_bf16_f32 v27, v8, v9
	global_store_dwordx4 v[44:45], v[24:27], off offset:96
	v_mov_b64_e32 v[8:9], v[202:203]
	v_mov_b64_e32 v[10:11], v[204:205]
	v_mov_b64_e32 v[20:21], v[198:199]
	v_mov_b64_e32 v[22:23], v[200:201]
	v_pk_mul_f32 v[12:13], v[2:3], v[16:17] op_sel_hi:[0,1]
	v_pk_mul_f32 v[12:13], v[12:13], v[20:21]
	v_pk_mul_f32 v[4:5], v[4:5], v[22:23]
	v_cvt_pk_bf16_f32 v12, v12, v13
	v_cvt_pk_bf16_f32 v13, v4, v5
	v_pk_mul_f32 v[4:5], v[2:3], v[18:19] op_sel_hi:[0,1]
	v_pk_mul_f32 v[4:5], v[4:5], v[8:9]
	v_lshl_add_u64 v[8:9], v[36:37], 0, s[6:7]
	v_cvt_pk_bf16_f32 v14, v4, v5
	v_pk_mul_f32 v[4:5], v[2:3], v[6:7] op_sel_hi:[0,1]
	v_pk_mul_f32 v[4:5], v[4:5], v[10:11]
	v_lshl_add_u64 v[8:9], v[8:9], 0, s[68:69]
	v_cvt_pk_bf16_f32 v15, v4, v5
	global_store_dwordx4 v[44:45], v[12:15], off offset:112
	s_waitcnt lgkmcnt(0)
	s_barrier
	ds_read_b128 v[4:7], v120
	v_lshl_add_u64 v[8:9], v[8:9], 0, v[42:43]
	s_waitcnt lgkmcnt(0)
	global_store_dwordx4 v[8:9], v[4:7], off
	ds_read_b128 v[4:7], v120 offset:9216
	v_lshl_add_u64 v[8:9], v[36:37], 0, s[16:17]
	v_lshl_add_u64 v[8:9], v[8:9], 0, s[68:69]
	v_lshl_add_u64 v[8:9], v[8:9], 0, v[42:43]
	s_waitcnt lgkmcnt(0)
	global_store_dwordx4 v[8:9], v[4:7], off
	ds_read_b128 v[4:7], v120 offset:18432
	v_lshl_add_u64 v[8:9], v[36:37], 0, s[18:19]
	v_lshl_add_u64 v[8:9], v[8:9], 0, s[68:69]
	v_lshl_add_u64 v[8:9], v[8:9], 0, v[42:43]
	s_waitcnt lgkmcnt(0)
	global_store_dwordx4 v[8:9], v[4:7], off
	ds_read_b128 v[4:7], v120 offset:27648
	v_lshl_add_u64 v[8:9], v[36:37], 0, s[4:5]
	v_lshl_add_u64 v[8:9], v[8:9], 0, s[68:69]
	v_lshl_add_u64 v[8:9], v[8:9], 0, v[42:43]
	s_waitcnt lgkmcnt(0)
	global_store_dwordx4 v[8:9], v[4:7], off
	ds_read_b128 v[4:7], v120 offset:36864
	v_lshl_add_u64 v[8:9], v[38:39], 0, s[6:7]
	v_lshl_add_u64 v[8:9], v[8:9], 0, s[68:69]
	v_lshl_add_u64 v[8:9], v[8:9], 0, v[42:43]
	s_waitcnt lgkmcnt(0)
	global_store_dwordx4 v[8:9], v[4:7], off
	ds_read_b128 v[4:7], v120 offset:46080
	v_lshl_add_u64 v[8:9], v[38:39], 0, s[16:17]
	v_lshl_add_u64 v[8:9], v[8:9], 0, s[68:69]
	v_lshl_add_u64 v[8:9], v[8:9], 0, v[42:43]
	s_waitcnt lgkmcnt(0)
	global_store_dwordx4 v[8:9], v[4:7], off
	ds_read_b128 v[4:7], v120 offset:55296
	v_lshl_add_u64 v[8:9], v[38:39], 0, s[18:19]
	v_lshl_add_u64 v[8:9], v[8:9], 0, s[68:69]
	v_lshl_add_u64 v[8:9], v[8:9], 0, v[42:43]
	s_waitcnt lgkmcnt(0)
	global_store_dwordx4 v[8:9], v[4:7], off
	ds_read_b128 v[4:7], v120 offset:64512
	v_lshl_add_u64 v[8:9], v[38:39], 0, s[4:5]
	v_lshl_add_u64 v[8:9], v[8:9], 0, s[68:69]
	v_lshl_add_u64 v[8:9], v[8:9], 0, v[42:43]
	s_waitcnt lgkmcnt(0)
	global_store_dwordx4 v[8:9], v[4:7], off
	s_barrier
	s_cbranch_scc1 .LBB0_691

; __device__ __forceinline__ float bflo(unsigned w) { return __uint_as_float(w << 16); }
; __device__ __forceinline__ float bfhi(unsigned w) { return __uint_as_float(w & 0xffff0000u); }
; __device__ __forceinline__ void norm64_inplace(bf16* p, const float* gain, float mult) {
;     u32x4 w[8]; float ss = 0.f;
; #pragma unroll
;     for (int k = 0; k < 8; ++k) { w[k] = ((const u32x4*)p)[k];
;         const float a0 = bflo(w[k].x), a1 = bfhi(w[k].x), a2 = bflo(w[k].y), a3 = bfhi(w[k].y), a4 = bflo(w[k].z), a5 = bfhi(w[k].z), a6 = bflo(w[k].w), a7 = bfhi(w[k].w);
;         ss += (a0 * a0 + a1 * a1) + (a2 * a2 + a3 * a3) + (a4 * a4 + a5 * a5) + (a6 * a6 + a7 * a7); }
;     const float r = rsqrtf(ss * (1.0f / 64.0f) + EPS) * mult;
; __device__ __forceinline__ void nsa_prep2_phase(bf16* z, const float* qg, const float* kg, bf16* vst, bf16* vwt, LAS unsigned char* lds, int tid, int u0, int ustride) {
;     ...
;         for (int v = tid; v < 1024; v += 512) { const int tok = v >> 4, hd = v & 15; norm64_inplace(z + (row0 + tok) * ZP + C_NQ + hd * 64, qg, 0.125f * LOG2E); }
.LBB0_690:
	v_ashrrev_i32_e32 v4, 4, v121
	v_ashrrev_i32_e32 v5, 31, v4
	v_lshl_add_u64 v[4:5], s[18:19], 0, v[4:5]
	v_mov_b64_e32 v[6:7], s[76:77]
	v_mad_u64_u32 v[6:7], s[4:5], v4, s88, v[6:7]
	v_mov_b32_e32 v2, v7
	v_mad_u64_u32 v[4:5], s[4:5], v5, s88, v[2:3]
	v_and_b32_e32 v2, 0x3c0, v43
	v_mov_b32_e32 v7, v4
	v_lshlrev_b32_e32 v2, 1, v2
	v_lshl_add_u64 v[4:5], v[6:7], 0, v[2:3]
	v_add_co_u32_e32 v64, vcc, s75, v4
	v_lshl_add_u64 v[44:45], v[4:5], 0, s[66:67]
	s_nop 0
	v_addc_co_u32_e32 v65, vcc, 0, v5, vcc
	global_load_dwordx4 v[130:133], v3, s[14:15]
	global_load_dwordx4 v[134:137], v3, s[14:15] offset:16
	global_load_dwordx4 v[138:141], v3, s[14:15] offset:32
	global_load_dwordx4 v[142:145], v3, s[14:15] offset:48
	global_load_dwordx4 v[146:149], v3, s[14:15] offset:64
	global_load_dwordx4 v[150:153], v3, s[14:15] offset:80
	global_load_dwordx4 v[154:157], v3, s[14:15] offset:96
	global_load_dwordx4 v[158:161], v3, s[14:15] offset:112
	global_load_dwordx4 v[162:165], v3, s[14:15] offset:128
	global_load_dwordx4 v[166:169], v3, s[14:15] offset:144
	global_load_dwordx4 v[170:173], v3, s[14:15] offset:160
	global_load_dwordx4 v[186:189], v3, s[14:15] offset:176
	global_load_dwordx4 v[190:193], v3, s[14:15] offset:192
	global_load_dwordx4 v[194:197], v3, s[14:15] offset:208
	global_load_dwordx4 v[198:201], v3, s[14:15] offset:224
	global_load_dwordx4 v[202:205], v3, s[14:15] offset:240
	global_load_dwordx4 v[26:29], v[64:65], off offset:1024
	global_load_dwordx4 v[16:19], v[44:45], off offset:48
	global_load_dwordx4 v[22:25], v[44:45], off offset:32
	global_load_dwordx4 v[4:7], v[44:45], off offset:16
	v_add_u32_e32 v43, 0x8000, v43
	s_waitcnt vmcnt(3)
	v_and_b32_e32 v83, 0xffff0000, v29
	v_and_b32_e32 v87, 0xffff0000, v28
	s_waitcnt vmcnt(1)
	v_lshlrev_b32_e32 v58, 16, v22
	s_waitcnt vmcnt(0)
	v_and_b32_e32 v63, 0xffff0000, v5
	v_and_b32_e32 v62, 0xffff0000, v4
	v_lshlrev_b32_e32 v101, 16, v5
	v_lshlrev_b32_e32 v100, 16, v4
	v_pk_mul_f32 v[4:5], v[62:63], v[62:63]
	v_and_b32_e32 v61, 0xffff0000, v7
	v_and_b32_e32 v60, 0xffff0000, v6
	v_pk_fma_f32 v[4:5], v[100:101], v[100:101], v[4:5]
	v_lshlrev_b32_e32 v103, 16, v7
	v_lshlrev_b32_e32 v102, 16, v6
	v_pk_mul_f32 v[6:7], v[60:61], v[60:61]
	v_pk_add_f32 v[4:5], v[4:5], v[4:5] op_sel:[0,1] op_sel_hi:[1,0]
	v_pk_fma_f32 v[6:7], v[102:103], v[102:103], v[6:7]
	v_and_b32_e32 v59, 0xffff0000, v22
	v_pk_add_f32 v[4:5], v[6:7], v[4:5]
	v_lshlrev_b32_e32 v56, 16, v23
	v_pk_add_f32 v[92:93], v[6:7], v[4:5] op_sel:[1,0] op_sel_hi:[0,1]
	v_and_b32_e32 v57, 0xffff0000, v23
	global_load_dwordx4 v[4:7], v[44:45], off offset:112
	global_load_dwordx4 v[20:23], v[44:45], off offset:96
	global_load_dwordx4 v[8:11], v[44:45], off offset:80
	global_load_dwordx4 v[12:15], v[44:45], off offset:64
	v_mul_f32_e32 v2, v59, v59
	v_pk_fma_f32 v[72:73], v[58:59], v[58:59], v[2:3] op_sel_hi:[1,1,0]
	v_mul_f32_e32 v2, v57, v57
	v_pk_fma_f32 v[84:85], v[56:57], v[56:57], v[2:3] op_sel_hi:[1,1,0]
	v_and_b32_e32 v99, 0xffff0000, v26
	v_lshlrev_b32_e32 v82, 16, v29
	v_lshlrev_b32_e32 v86, 16, v28
	v_and_b32_e32 v89, 0xffff0000, v27
	v_lshlrev_b32_e32 v98, 16, v26
	v_mov_b32_e32 v76, v87
	v_mov_b32_e32 v77, v99
	v_lshlrev_b32_e32 v88, 16, v27
	v_mov_b32_e32 v26, v86
	v_mov_b32_e32 v27, v98
	v_pk_mul_f32 v[76:77], v[76:77], v[76:77]
	v_lshlrev_b32_e32 v125, 16, v18
	v_pk_fma_f32 v[26:27], v[26:27], v[26:27], v[76:77]
	v_mov_b32_e32 v110, v100
	v_lshlrev_b32_e32 v100, 16, v19
	v_mov_b32_e32 v111, v62
	v_mov_b32_e32 v62, v101
	v_lshlrev_b32_e32 v123, 16, v16
	v_and_b32_e32 v81, 0xffff0000, v16
	v_and_b32_e32 v80, 0xffff0000, v24
	v_lshlrev_b32_e32 v122, 16, v24
	v_lshlrev_b32_e32 v124, 16, v25
	v_mov_b32_e32 v108, v102
	v_mov_b32_e32 v109, v60
	v_mov_b32_e32 v60, v103
	v_mov_b32_e32 v102, v124
	s_waitcnt vmcnt(2)
	v_and_b32_e32 v47, 0xffff0000, v20
	s_waitcnt vmcnt(1)
	v_and_b32_e32 v51, 0xffff0000, v9
	s_waitcnt vmcnt(0)
	v_and_b32_e32 v55, 0xffff0000, v13
	v_and_b32_e32 v54, 0xffff0000, v12
	v_and_b32_e32 v50, 0xffff0000, v8
	v_lshlrev_b32_e32 v79, 16, v13
	v_lshlrev_b32_e32 v78, 16, v12
	v_pk_mul_f32 v[12:13], v[54:55], v[54:55]
	v_and_b32_e32 v53, 0xffff0000, v15
	v_and_b32_e32 v52, 0xffff0000, v14
	v_lshlrev_b32_e32 v95, 16, v9
	v_lshlrev_b32_e32 v94, 16, v8
	v_pk_mul_f32 v[8:9], v[50:51], v[50:51]
	v_and_b32_e32 v49, 0xffff0000, v11
	v_and_b32_e32 v48, 0xffff0000, v10
	v_pk_fma_f32 v[12:13], v[78:79], v[78:79], v[12:13]
	v_lshlrev_b32_e32 v91, 16, v15
	v_lshlrev_b32_e32 v90, 16, v14
	v_pk_mul_f32 v[14:15], v[52:53], v[52:53]
	v_pk_fma_f32 v[8:9], v[94:95], v[94:95], v[8:9]
	v_lshlrev_b32_e32 v97, 16, v11
	v_lshlrev_b32_e32 v96, 16, v10
	v_pk_mul_f32 v[10:11], v[48:49], v[48:49]
	v_pk_add_f32 v[12:13], v[12:13], v[12:13] op_sel:[0,1] op_sel_hi:[1,0]
	v_pk_fma_f32 v[14:15], v[90:91], v[90:91], v[14:15]
	v_pk_add_f32 v[8:9], v[8:9], v[8:9] op_sel:[0,1] op_sel_hi:[1,0]
	v_pk_fma_f32 v[10:11], v[96:97], v[96:97], v[10:11]
	v_pk_add_f32 v[12:13], v[14:15], v[12:13]
	v_pk_add_f32 v[8:9], v[10:11], v[8:9]
	v_pk_add_f32 v[70:71], v[14:15], v[12:13] op_sel:[1,0] op_sel_hi:[0,1]
	v_pk_add_f32 v[74:75], v[10:11], v[8:9] op_sel:[1,0] op_sel_hi:[0,1]
	s_waitcnt vmcnt(0)
; __device__ __forceinline__ float bflo(unsigned w) { return __uint_as_float(w << 16); }
; __device__ __forceinline__ float bfhi(unsigned w) { return __uint_as_float(w & 0xffff0000u); }
; __device__ __forceinline__ unsigned pk2(float lo, float hi) { return pg8::cvt_pk_bf16(lo, hi); }
; __device__ __forceinline__ void norm64_inplace(bf16* p, const float* gain, float mult) {
;     ...
;     const float r = rsqrtf(ss * (1.0f / 64.0f) + EPS) * mult;
; #pragma unroll
;     for (int k = 0; k < 8; ++k) { const f32x4 g0 = *(const f32x4*)(gain + 8 * k), g1 = *(const f32x4*)(gain + 8 * k + 4);
;         u32x4 o; o.x = pk2(bflo(w[k].x) * r * g0[0], bfhi(w[k].x) * r * g0[1]); o.y = pk2(bflo(w[k].y) * r * g0[2], bfhi(w[k].y) * r * g0[3]);
;         o.z = pk2(bflo(w[k].z) * r * g1[0], bfhi(w[k].z) * r * g1[1]); o.w = pk2(bflo(w[k].w) * r * g1[2], bfhi(w[k].w) * r * g1[3]);
;         ((u32x4*)p)[k] = o; }
; __device__ __forceinline__ void nsa_prep2_phase(bf16* z, const float* qg, const float* kg, bf16* vst, bf16* vwt, LAS unsigned char* lds, int tid, int u0, int ustride) {
;     ...
;         for (int v = tid; v < 1024; v += 512) { const int tok = v >> 4, hd = v & 15; norm64_inplace(z + (row0 + tok) * ZP + C_NQ + hd * 64, qg, 0.125f * LOG2E); }
	v_mov_b64_e32 v[8:9], v[134:135]
	v_mov_b64_e32 v[10:11], v[136:137]
	v_mov_b64_e32 v[12:13], v[130:131]
	v_mov_b64_e32 v[14:15], v[132:133]
	v_lshlrev_b32_e32 v46, 16, v20
	v_mul_f32_e32 v2, v47, v47
	v_lshlrev_b32_e32 v20, 16, v21
	v_and_b32_e32 v21, 0xffff0000, v21
	v_pk_fma_f32 v[66:67], v[46:47], v[46:47], v[2:3] op_sel_hi:[1,1,0]
	v_mul_f32_e32 v2, v21, v21
	v_pk_fma_f32 v[68:69], v[20:21], v[20:21], v[2:3] op_sel_hi:[1,1,0]
	v_mul_f32_e32 v2, v83, v83
	v_pk_fma_f32 v[106:107], v[82:83], v[82:83], v[2:3] op_sel_hi:[1,1,0]
	v_mul_f32_e32 v2, v89, v89
	v_pk_fma_f32 v[28:29], v[88:89], v[88:89], v[2:3] op_sel_hi:[1,1,0]
	v_pk_mov_b32 v[104:105], v[22:23], v[6:7] op_sel:[1,0]
	v_pk_add_f32 v[28:29], v[26:27], v[28:29] op_sel:[1,0] op_sel_hi:[0,1]
	v_pk_add_f32 v[116:117], v[26:27], v[28:29]
	v_pk_mov_b32 v[26:27], v[24:25], v[18:19] op_sel:[1,0]
	v_and_b32_e32 v19, 0xffff0000, v19
	v_and_b32_e32 v18, s0, v18
	v_mov_b32_e32 v101, v19
	v_pk_mul_f32 v[18:19], v[18:19], v[18:19]
	v_pk_add_f32 v[106:107], v[106:107], v[116:117]
	v_mov_b32_e32 v93, v19
	v_mul_f32_e32 v107, v100, v100
	v_pk_add_f32 v[18:19], v[106:107], v[92:93]
	v_lshlrev_b32_e32 v106, 16, v17
	v_and_b32_e32 v107, 0xffff0000, v17
	v_pk_mul_f32 v[16:17], v[106:107], v[106:107]
	v_and_b32_e32 v77, 0xffff0000, v27
	v_and_b32_e32 v76, 0xffff0000, v26
	v_pk_mul_f32 v[24:25], v[80:81], v[80:81]
	v_mov_b32_e32 v73, v16
	v_mov_b32_e32 v85, v17
	v_pk_fma_f32 v[126:127], v[122:123], v[122:123], v[24:25]
	v_pk_mul_f32 v[24:25], v[76:77], v[76:77]
	v_pk_add_f32 v[16:17], v[72:73], v[84:85]
	v_pk_fma_f32 v[128:129], v[124:125], v[124:125], v[24:25]
	v_pk_add_f32 v[16:17], v[126:127], v[16:17]
	v_lshlrev_b32_e32 v29, 16, v6
	v_pk_add_f32 v[16:17], v[128:129], v[16:17]
	v_lshlrev_b32_e32 v6, 16, v7
	v_pk_add_f32 v[16:17], v[18:19], v[16:17]
	v_and_b32_e32 v7, 0xffff0000, v7
	v_pk_add_f32 v[116:117], v[16:17], v[16:17] op_sel:[0,1] op_sel_hi:[1,0]
	v_lshlrev_b32_e32 v25, 16, v4
	v_pk_add_f32 v[70:71], v[116:117], v[70:71]
	v_and_b32_e32 v27, 0xffff0000, v4
	v_mul_f32_e32 v75, v7, v7
	v_mul_f32_e32 v71, v6, v6
	v_lshlrev_b32_e32 v4, 16, v5
	v_and_b32_e32 v5, 0xffff0000, v5
	v_and_b32_e32 v26, 0xffff0000, v22
	v_pk_add_f32 v[70:71], v[70:71], v[74:75]
	v_pk_mul_f32 v[74:75], v[4:5], v[4:5]
	v_lshlrev_b32_e32 v24, 16, v22
	v_lshlrev_b32_e32 v28, 16, v23
	v_and_b32_e32 v23, 0xffff0000, v105
	v_and_b32_e32 v22, 0xffff0000, v104
	v_pk_mul_f32 v[104:105], v[26:27], v[26:27]
	v_mov_b32_e32 v67, v74
	v_mov_b32_e32 v69, v75
	v_pk_fma_f32 v[114:115], v[24:25], v[24:25], v[104:105]
	v_pk_mul_f32 v[104:105], v[22:23], v[22:23]
	v_pk_add_f32 v[66:67], v[66:67], v[68:69]
	v_pk_fma_f32 v[112:113], v[28:29], v[28:29], v[104:105]
	v_pk_add_f32 v[66:67], v[114:115], v[66:67]
	v_mov_b32_e32 v17, v22
	v_pk_add_f32 v[66:67], v[112:113], v[66:67]
	v_mov_b32_e32 v104, v122
	v_pk_add_f32 v[66:67], v[70:71], v[66:67]
	v_mov_b32_e32 v105, v80
	v_add_f32_e32 v2, v66, v67
	v_fmamk_f32 v2, v2, 0x3c800000, v213
	v_cmp_gt_f32_e32 vcc, s83, v2
	v_mul_f32_e32 v22, 0x4b800000, v2
	v_mov_b32_e32 v103, v76
	v_cndmask_b32_e32 v2, v2, v22, vcc
	v_rsq_f32_e32 v2, v2
	v_mov_b32_e32 v80, v123
	v_mov_b32_e32 v76, v125
	v_mov_b32_e32 v92, v78
	v_mul_f32_e32 v22, 0x45800000, v2
	v_cndmask_b32_e32 v2, v2, v22, vcc
	v_mul_f32_e32 v2, 0x3e38aa3b, v2
	v_pk_mul_f32 v[66:67], v[2:3], v[98:99] op_sel_hi:[0,1]
	v_pk_mul_f32 v[12:13], v[12:13], v[66:67]
	v_pk_mul_f32 v[66:67], v[2:3], v[88:89] op_sel_hi:[0,1]
	v_pk_mul_f32 v[14:15], v[14:15], v[66:67]
	v_cvt_pk_bf16_f32 v12, v12, v13
	v_cvt_pk_bf16_f32 v13, v14, v15
	v_pk_mul_f32 v[14:15], v[2:3], v[86:87] op_sel_hi:[0,1]
	v_pk_mul_f32 v[8:9], v[8:9], v[14:15]
	v_pk_mul_f32 v[62:63], v[2:3], v[62:63] op_sel_hi:[0,1]
	v_cvt_pk_bf16_f32 v14, v8, v9
	v_pk_mul_f32 v[8:9], v[2:3], v[82:83] op_sel_hi:[0,1]
	v_pk_mul_f32 v[8:9], v[10:11], v[8:9]
	v_pk_mul_f32 v[58:59], v[2:3], v[58:59] op_sel_hi:[0,1]
	v_cvt_pk_bf16_f32 v15, v8, v9
	global_store_dwordx4 v[64:65], v[12:15], off offset:1024
	v_mov_b64_e32 v[8:9], v[142:143]
	v_mov_b64_e32 v[10:11], v[144:145]
	s_nop 0
	v_mov_b64_e32 v[12:13], v[138:139]
	v_mov_b64_e32 v[14:15], v[140:141]
	v_pk_mul_f32 v[64:65], v[2:3], v[110:111] op_sel_hi:[0,1]
	v_pk_mul_f32 v[56:57], v[2:3], v[56:57] op_sel_hi:[0,1]
	v_mov_b32_e32 v93, v54
	v_mov_b32_e32 v54, v79
	v_pk_mul_f32 v[54:55], v[2:3], v[54:55] op_sel_hi:[0,1]
	v_mov_b32_e32 v84, v90
	v_mov_b32_e32 v85, v52
	v_mov_b32_e32 v52, v91
	v_mov_b32_e32 v78, v94
	v_mov_b32_e32 v79, v50
	v_mov_b32_e32 v50, v95
	v_pk_mul_f32 v[50:51], v[2:3], v[50:51] op_sel_hi:[0,1]
	v_mov_b32_e32 v72, v96
	v_mov_b32_e32 v73, v48
	v_mov_b32_e32 v48, v97
	v_pk_mul_f32 v[46:47], v[2:3], v[46:47] op_sel_hi:[0,1]
	v_pk_mul_f32 v[20:21], v[2:3], v[20:21] op_sel_hi:[0,1]
	v_mov_b32_e32 v18, v24
	v_mov_b32_e32 v19, v26
; __device__ __forceinline__ float bflo(unsigned w) { return __uint_as_float(w << 16); }
; __device__ __forceinline__ float bfhi(unsigned w) { return __uint_as_float(w & 0xffff0000u); }
; __device__ __forceinline__ unsigned pk2(float lo, float hi) { return pg8::cvt_pk_bf16(lo, hi); }
; __device__ __forceinline__ void norm64_inplace(bf16* p, const float* gain, float mult) {
;     ...
;     for (int k = 0; k < 8; ++k) { const f32x4 g0 = *(const f32x4*)(gain + 8 * k), g1 = *(const f32x4*)(gain + 8 * k + 4);
;         u32x4 o; o.x = pk2(bflo(w[k].x) * r * g0[0], bfhi(w[k].x) * r * g0[1]); o.y = pk2(bflo(w[k].y) * r * g0[2], bfhi(w[k].y) * r * g0[3]);
;         o.z = pk2(bflo(w[k].z) * r * g1[0], bfhi(w[k].z) * r * g1[1]); o.w = pk2(bflo(w[k].w) * r * g1[2], bfhi(w[k].w) * r * g1[3]);
;         ((u32x4*)p)[k] = o; }
; __device__ __forceinline__ void nsa_prep2_phase(bf16* z, const float* qg, const float* kg, bf16* vst, bf16* vwt, LAS unsigned char* lds, int tid, int u0, int ustride) {
;     ...
;         for (int v = tid; v < 1024; v += 512) { const int tok = v >> 4, hd = v & 15; norm64_inplace(z + (row0 + tok) * ZP + C_NQ + hd * 64, qg, 0.125f * LOG2E); }
	v_mov_b32_e32 v16, v28
	v_mov_b32_e32 v26, v25
	v_pk_mul_f32 v[4:5], v[2:3], v[4:5] op_sel_hi:[0,1]
	v_mov_b32_e32 v22, v29
	v_cmp_lt_i32_e32 vcc, s93, v121
	s_or_b64 s[22:23], vcc, s[22:23]
	v_pk_mul_f32 v[12:13], v[12:13], v[64:65]
	v_pk_mul_f32 v[14:15], v[14:15], v[62:63]
	v_cvt_pk_bf16_f32 v12, v12, v13
	v_cvt_pk_bf16_f32 v13, v14, v15
	v_pk_mul_f32 v[14:15], v[2:3], v[108:109] op_sel_hi:[0,1]
	v_pk_mul_f32 v[8:9], v[8:9], v[14:15]
	s_nop 0
	v_cvt_pk_bf16_f32 v14, v8, v9
	v_pk_mul_f32 v[8:9], v[2:3], v[60:61] op_sel_hi:[0,1]
	v_pk_mul_f32 v[8:9], v[10:11], v[8:9]
	s_nop 0
	v_cvt_pk_bf16_f32 v15, v8, v9
	global_store_dwordx4 v[44:45], v[12:15], off offset:16
	v_mov_b64_e32 v[8:9], v[150:151]
	v_mov_b64_e32 v[10:11], v[152:153]
	s_nop 0
	v_mov_b64_e32 v[12:13], v[146:147]
	v_mov_b64_e32 v[14:15], v[148:149]
	v_pk_mul_f32 v[12:13], v[12:13], v[58:59]
	v_pk_mul_f32 v[14:15], v[14:15], v[56:57]
	v_cvt_pk_bf16_f32 v12, v12, v13
	v_cvt_pk_bf16_f32 v13, v14, v15
	v_pk_mul_f32 v[14:15], v[2:3], v[104:105] op_sel_hi:[0,1]
	v_pk_mul_f32 v[8:9], v[8:9], v[14:15]
	v_pk_mul_f32 v[56:57], v[2:3], v[80:81] op_sel_hi:[0,1]
	v_cvt_pk_bf16_f32 v14, v8, v9
	v_pk_mul_f32 v[8:9], v[2:3], v[102:103] op_sel_hi:[0,1]
	v_pk_mul_f32 v[8:9], v[10:11], v[8:9]
	s_nop 0
	v_cvt_pk_bf16_f32 v15, v8, v9
	global_store_dwordx4 v[44:45], v[12:15], off offset:32
	v_mov_b64_e32 v[8:9], v[158:159]
	v_mov_b64_e32 v[10:11], v[160:161]
	s_nop 0
	v_mov_b64_e32 v[12:13], v[154:155]
	v_mov_b64_e32 v[14:15], v[156:157]
	v_pk_mul_f32 v[12:13], v[12:13], v[56:57]
	v_pk_mul_f32 v[56:57], v[2:3], v[106:107] op_sel_hi:[0,1]
	v_pk_mul_f32 v[14:15], v[14:15], v[56:57]
	v_cvt_pk_bf16_f32 v12, v12, v13
	v_cvt_pk_bf16_f32 v13, v14, v15
	v_pk_mul_f32 v[14:15], v[2:3], v[76:77] op_sel_hi:[0,1]
	v_pk_mul_f32 v[8:9], v[8:9], v[14:15]
	v_pk_mul_f32 v[56:57], v[2:3], v[92:93] op_sel_hi:[0,1]
	v_cvt_pk_bf16_f32 v14, v8, v9
	v_pk_mul_f32 v[8:9], v[2:3], v[100:101] op_sel_hi:[0,1]
	v_pk_mul_f32 v[8:9], v[10:11], v[8:9]
	s_nop 0
	v_cvt_pk_bf16_f32 v15, v8, v9
	global_store_dwordx4 v[44:45], v[12:15], off offset:48
	v_mov_b64_e32 v[8:9], v[166:167]
	v_mov_b64_e32 v[10:11], v[168:169]
	s_nop 0
	v_mov_b64_e32 v[12:13], v[162:163]
	v_mov_b64_e32 v[14:15], v[164:165]
	v_pk_mul_f32 v[12:13], v[12:13], v[56:57]
	v_pk_mul_f32 v[14:15], v[14:15], v[54:55]
	v_cvt_pk_bf16_f32 v12, v12, v13
	v_cvt_pk_bf16_f32 v13, v14, v15
	v_pk_mul_f32 v[14:15], v[2:3], v[84:85] op_sel_hi:[0,1]
	v_pk_mul_f32 v[8:9], v[8:9], v[14:15]
	s_nop 0
	v_cvt_pk_bf16_f32 v14, v8, v9
	v_pk_mul_f32 v[8:9], v[2:3], v[52:53] op_sel_hi:[0,1]
	v_pk_mul_f32 v[8:9], v[10:11], v[8:9]
	v_pk_mul_f32 v[52:53], v[2:3], v[78:79] op_sel_hi:[0,1]
	v_cvt_pk_bf16_f32 v15, v8, v9
	global_store_dwordx4 v[44:45], v[12:15], off offset:64
	v_mov_b64_e32 v[8:9], v[186:187]
	v_mov_b64_e32 v[10:11], v[188:189]
	s_nop 0
	v_mov_b64_e32 v[12:13], v[170:171]
	v_mov_b64_e32 v[14:15], v[172:173]
	v_pk_mul_f32 v[12:13], v[12:13], v[52:53]
	v_pk_mul_f32 v[14:15], v[14:15], v[50:51]
	v_cvt_pk_bf16_f32 v12, v12, v13
	v_cvt_pk_bf16_f32 v13, v14, v15
	v_pk_mul_f32 v[14:15], v[2:3], v[72:73] op_sel_hi:[0,1]
	v_pk_mul_f32 v[8:9], v[14:15], v[8:9]
	s_nop 0
	v_cvt_pk_bf16_f32 v14, v8, v9
	v_pk_mul_f32 v[8:9], v[2:3], v[48:49] op_sel_hi:[0,1]
	v_pk_mul_f32 v[8:9], v[8:9], v[10:11]
	s_nop 0
	v_cvt_pk_bf16_f32 v15, v8, v9
	global_store_dwordx4 v[44:45], v[12:15], off offset:80
	v_mov_b64_e32 v[8:9], v[194:195]
	v_mov_b64_e32 v[10:11], v[196:197]
	s_nop 0
	v_mov_b64_e32 v[12:13], v[190:191]
	v_mov_b64_e32 v[14:15], v[192:193]
	v_pk_mul_f32 v[12:13], v[46:47], v[12:13]
	v_pk_mul_f32 v[14:15], v[20:21], v[14:15]
	v_cvt_pk_bf16_f32 v12, v12, v13
	v_cvt_pk_bf16_f32 v13, v14, v15
	v_pk_mul_f32 v[14:15], v[2:3], v[18:19] op_sel_hi:[0,1]
	v_pk_mul_f32 v[8:9], v[14:15], v[8:9]
	s_nop 0
	v_cvt_pk_bf16_f32 v14, v8, v9
	v_pk_mul_f32 v[8:9], v[2:3], v[16:17] op_sel_hi:[0,1]
	v_pk_mul_f32 v[8:9], v[8:9], v[10:11]
	v_pk_mul_f32 v[16:17], v[2:3], v[26:27] op_sel_hi:[0,1]
	v_cvt_pk_bf16_f32 v15, v8, v9
	global_store_dwordx4 v[44:45], v[12:15], off offset:96
	v_mov_b64_e32 v[8:9], v[202:203]
	v_mov_b64_e32 v[10:11], v[204:205]
	s_nop 0
	v_mov_b64_e32 v[12:13], v[198:199]
	v_mov_b64_e32 v[14:15], v[200:201]
	v_pk_mul_f32 v[12:13], v[16:17], v[12:13]
	v_pk_mul_f32 v[4:5], v[4:5], v[14:15]
	v_cvt_pk_bf16_f32 v12, v12, v13
	v_cvt_pk_bf16_f32 v13, v4, v5
	v_pk_mul_f32 v[4:5], v[2:3], v[22:23] op_sel_hi:[0,1]
	v_pk_mul_f32 v[4:5], v[4:5], v[8:9]
	s_nop 0
	v_cvt_pk_bf16_f32 v14, v4, v5
	v_pk_mul_f32 v[4:5], v[2:3], v[6:7] op_sel_hi:[0,1]
	v_pk_mul_f32 v[4:5], v[4:5], v[10:11]
	v_add_u32_e32 v2, 0x200, v121
	v_cvt_pk_bf16_f32 v15, v4, v5
	v_mov_b32_e32 v121, v2
	global_store_dwordx4 v[44:45], v[12:15], off offset:112
	s_andn2_b64 exec, exec, s[22:23]
	s_cbranch_execnz .LBB0_690
	s_branch .LBB0_687

; __device__ __forceinline__ void hgrn_rec_phase(const bf16* z, const bf16* hq, const float* dd, float* oraw, LAS unsigned char* lds, int tid0, int G) {
;     ...
;         for (int c = 0; c < 64; ++c) {
;     ...
;             if (act && c + 1 < 64) HG_STORE((c + 1) & 1);
;             sQ = tQ; sK = tK; sH = tH; sI = tI; sD = tD;
;             __syncthreads();
.LBB0_729:
	s_mov_b64 s[6:7], 0x200
	s_add_i32 s0, s0, 1
	v_lshl_add_u64 v[192:193], v[192:193], 0, s[6:7]
	s_mov_b64 s[6:7], 0x10000
	s_and_b64 vcc, exec, s[4:5]
	s_cbranch_vccz .Lrec_stgw
	s_waitcnt vmcnt(4)
	s_branch .Lrec_cpy

; __device__ __forceinline__ void hgrn_rec_phase(const bf16* z, const bf16* hq, const float* dd, float* oraw, LAS unsigned char* lds, int tid0, int G) {
;     ...
;             sQ = tQ; sK = tK; sH = tH; sI = tI; sD = tD;
;             __syncthreads();
.Lrec_cpy:
	v_mov_b64_e32 v[152:153], v[10:11]
	v_mov_b64_e32 v[156:157], v[14:15]
	v_mov_b64_e32 v[158:159], v[166:167]
	v_mov_b64_e32 v[162:163], v[170:171]
	v_mov_b64_e32 v[148:149], v[6:7]
	v_lshl_add_u64 v[194:195], v[194:195], 0, s[60:61]
	v_lshl_add_u64 v[196:197], v[196:197], 0, s[60:61]
	v_lshl_add_u64 v[198:199], v[198:199], 0, s[6:7]
	s_cmp_lg_u32 s0, 64
	v_mov_b64_e32 v[150:151], v[8:9]
	v_mov_b64_e32 v[154:155], v[12:13]
	v_mov_b64_e32 v[160:161], v[168:169]
	v_mov_b64_e32 v[164:165], v[172:173]
	v_mov_b64_e32 v[146:147], v[4:5]
	s_waitcnt lgkmcnt(0)
	s_barrier
	s_cbranch_scc0 .LBB0_739

; __device__ __forceinline__ void hgrn_rec_phase(const bf16* z, const bf16* hq, const float* dd, float* oraw, LAS unsigned char* lds, int tid0, int G) {
;     ...
;             if (act && c + 1 < 64) HG_STORE((c + 1) & 1);
.LBB0_736:
	s_cmp_eq_u32 s0, 63
	s_cselect_b64 s[44:45], -1, 0
	s_xor_b64 s[6:7], s[6:7], -1
	s_or_b64 s[6:7], s[44:45], s[6:7]
	s_and_b64 vcc, exec, s[6:7]
	s_cbranch_vccnz .LBB0_729
	s_andn2_b32 s1, 1, s0
	s_mul_i32 s1, s1, 0xb800
	s_add_i32 s1, s1, 0
	v_add3_u32 v2, s1, v1, v186
	s_waitcnt vmcnt(4)
	ds_write_b128 v2, v[150:153]
	ds_write_b128 v2, v[154:157] offset:8704
	v_add3_u32 v2, s1, v187, v188
	ds_write_b128 v2, v[158:161] offset:26112
	ds_write_b128 v2, v[162:165] offset:36352
	s_and_saveexec_b64 s[6:7], s[8:9]
	s_cbranch_execz .LBB0_728
	v_add_u32_e32 v2, s1, v202
	ds_write_b128 v2, v[146:149] offset:46592
	s_branch .LBB0_728
